# row passes: 64-lane butterfly sums via DPP quad_perm/row mirrors + permlane16/32 swaps instead of six ds_bpermute round trips (same partners and order)
# speedup vs baseline: 1.0004x; 1.0004x over previous
.LBB0_123:
	v_pk_mul_f32 v[104:105], v[126:127], v[126:127]
	v_pk_mul_f32 v[106:107], v[124:125], v[124:125]
	v_pk_mul_f32 v[96:97], v[122:123], v[122:123]
	v_pk_mul_f32 v[98:99], v[120:121], v[120:121]
	v_pk_mov_b32 v[108:109], v[106:107], v[104:105] op_sel:[1,0]
	v_mov_b32_e32 v107, v105
	v_pk_add_f32 v[104:105], v[108:109], v[106:107]
	v_pk_mov_b32 v[106:107], v[98:99], v[96:97] op_sel:[1,0]
	v_mov_b32_e32 v99, v97
	v_mul_f32_e32 v0, v116, v116
	v_pk_add_f32 v[96:97], v[106:107], v[98:99]
	v_pk_fma_f32 v[98:99], v[116:117], v[116:117], v[0:1] op_sel_hi:[1,1,0]
	v_mul_f32_e32 v0, v118, v118
	v_pk_add_f32 v[104:105], v[104:105], v[104:105] op_sel_hi:[0,1]
	v_pk_add_f32 v[96:97], v[96:97], v[96:97] op_sel_hi:[0,1]
	v_pk_fma_f32 v[106:107], v[118:119], v[118:119], v[0:1] op_sel_hi:[1,1,0]
	v_mul_f32_e32 v98, v132, v132
	v_mul_f32_e32 v106, v133, v133
	v_mul_f32_e32 v104, v134, v134
	v_mul_f32_e32 v96, v135, v135
	v_pk_add_f32 v[98:99], v[98:99], v[106:107]
	v_pk_add_f32 v[96:97], v[104:105], v[96:97]
	s_add_u32 s24, s24, 1
	v_pk_add_f32 v[96:97], v[98:99], v[96:97]
	s_addc_u32 s25, s25, 0
	v_add_f32_e32 v0, v96, v97
	s_nop 1
	v_mov_b32_dpp v96, v0 quad_perm:[1,0,3,2] row_mask:0xf bank_mask:0xf
	s_lshl_b64 s[26:27], s[4:5], 11
	v_pk_add_f32 v[108:109], v[52:53], 1.0 op_sel_hi:[1,0]
	s_waitcnt vmcnt(0)
	v_mov_b64_e32 v[114:115], v[102:103]
	v_lshl_add_u64 v[140:141], v[140:141], 0, s[64:65]
	s_waitcnt lgkmcnt(0)
	v_add_f32_e32 v0, v0, v96
	s_nop 1
	v_mov_b32_dpp v96, v0 quad_perm:[2,3,0,1] row_mask:0xf bank_mask:0xf
	v_lshl_add_u64 v[142:143], v[142:143], 0, s[64:65]
	v_lshl_add_u64 v[144:145], v[144:145], 0, s[60:61]
	s_cmp_lt_i32 s24, s2
	v_mov_b64_e32 v[112:113], v[100:101]
	s_waitcnt lgkmcnt(0)
	v_add_f32_e32 v0, v0, v96
	s_nop 1
	v_mov_b32_dpp v96, v0 row_half_mirror row_mask:0xf bank_mask:0xf
	v_mov_b64_e32 v[132:133], v[2:3]
	s_waitcnt lgkmcnt(0)
	v_add_f32_e32 v0, v0, v96
	s_nop 1
	v_mov_b32_dpp v96, v0 row_mirror row_mask:0xf bank_mask:0xf
	s_waitcnt lgkmcnt(0)
	v_add_f32_e32 v0, v0, v96
	v_mov_b32_e32 v96, v0
	s_nop 1
	v_permlane16_swap_b32_e32 v96, v0
	s_waitcnt lgkmcnt(0)
	v_add_f32_e32 v0, v0, v96
	v_mov_b32_e32 v96, v0
	s_nop 1
	v_permlane32_swap_b32_e32 v96, v0
	s_waitcnt lgkmcnt(0)
	v_add_f32_e32 v0, v0, v96
	v_fmamk_f32 v0, v0, 0x3a800000, v196
	v_mul_f32_e32 v96, 0x4f800000, v0
	v_cmp_gt_f32_e32 vcc, s3, v0
	s_nop 1
	v_cndmask_b32_e32 v0, v0, v96, vcc
	v_sqrt_f32_e32 v96, v0
	s_nop 0
	v_add_u32_e32 v97, -1, v96
	v_add_u32_e32 v98, 1, v96
	v_fma_f32 v99, -v97, v96, v0
	v_fma_f32 v104, -v98, v96, v0
	v_cmp_ge_f32_e64 s[4:5], 0, v99
	s_nop 1
	v_cndmask_b32_e64 v96, v96, v97, s[4:5]
	v_cmp_lt_f32_e64 s[4:5], 0, v104
	s_nop 1
	v_cndmask_b32_e64 v96, v96, v98, s[4:5]
	v_mul_f32_e32 v97, 0x37800000, v96
	v_cndmask_b32_e32 v96, v96, v97, vcc
	v_cmp_class_f32_e32 vcc, v0, v197
	s_nop 1
	v_cndmask_b32_e32 v0, v96, v0, vcc
	v_div_scale_f32 v98, s[4:5], v0, v0, 1.0
	v_rcp_f32_e32 v99, v98
	v_div_scale_f32 v104, vcc, 1.0, v0, 1.0
	v_lshl_add_u64 v[96:97], v[138:139], 0, s[26:27]
	v_fma_f32 v105, -v98, v99, 1.0
	v_fmac_f32_e32 v99, v105, v99
	v_mul_f32_e32 v105, v104, v99
	v_fma_f32 v106, -v98, v105, v104
	v_fmac_f32_e32 v105, v106, v99
	v_fma_f32 v98, -v98, v105, v104
	v_div_fmas_f32 v98, v98, v99, v105
	v_div_fixup_f32 v0, v98, v0, 1.0
	v_pk_mul_f32 v[104:105], v[124:125], v[0:1] op_sel_hi:[1,0]
	v_pk_mul_f32 v[98:99], v[126:127], v[0:1] op_sel_hi:[1,0]
	v_pk_mul_f32 v[104:105], v[12:13], v[104:105]
	v_pk_mul_f32 v[98:99], v[14:15], v[98:99]
	v_pk_add_f32 v[106:107], v[54:55], 1.0 op_sel_hi:[1,0]
	v_pk_fma_f32 v[104:105], v[108:109], v[104:105], v[56:57]
	v_pk_fma_f32 v[98:99], v[106:107], v[98:99], v[58:59]
	v_bfe_u32 v106, v104, 16, 1
	v_add3_u32 v104, v104, v106, s48
	v_bfe_u32 v106, v105, 16, 1
	v_lshrrev_b32_e32 v104, 16, v104
	v_add3_u32 v105, v105, v106, s48
	v_and_or_b32 v104, v105, s55, v104
	v_bfe_u32 v105, v98, 16, 1
	v_add3_u32 v98, v98, v105, s48
	v_bfe_u32 v105, v99, 16, 1
	v_lshrrev_b32_e32 v98, 16, v98
	v_add3_u32 v99, v99, v105, s48
	v_and_or_b32 v105, v99, s55, v98
	global_store_dwordx2 v[96:97], v[104:105], off
	v_pk_mul_f32 v[104:105], v[120:121], v[0:1] op_sel_hi:[1,0]
	v_pk_mul_f32 v[98:99], v[122:123], v[0:1] op_sel_hi:[1,0]
	v_pk_mul_f32 v[104:105], v[16:17], v[104:105]
	v_pk_add_f32 v[108:109], v[60:61], 1.0 op_sel_hi:[1,0]
	v_pk_mul_f32 v[98:99], v[18:19], v[98:99]
	v_pk_add_f32 v[106:107], v[62:63], 1.0 op_sel_hi:[1,0]
	v_pk_fma_f32 v[104:105], v[108:109], v[104:105], v[64:65]
	v_pk_fma_f32 v[98:99], v[106:107], v[98:99], v[66:67]
	v_bfe_u32 v106, v104, 16, 1
	v_add3_u32 v104, v104, v106, s48
	v_bfe_u32 v106, v105, 16, 1
	v_lshrrev_b32_e32 v104, 16, v104
	v_add3_u32 v105, v105, v106, s48
	v_and_or_b32 v104, v105, s55, v104
	v_bfe_u32 v105, v98, 16, 1
	v_add3_u32 v98, v98, v105, s48
	v_bfe_u32 v105, v99, 16, 1
	v_lshrrev_b32_e32 v98, 16, v98
	v_add3_u32 v99, v99, v105, s48
	v_and_or_b32 v105, v99, s55, v98
	global_store_dwordx2 v[96:97], v[104:105], off offset:512
	v_pk_mul_f32 v[104:105], v[116:117], v[0:1] op_sel_hi:[1,0]
	v_pk_mul_f32 v[98:99], v[118:119], v[0:1] op_sel_hi:[1,0]
	v_pk_mul_f32 v[104:105], v[28:29], v[104:105]
	v_pk_add_f32 v[108:109], v[68:69], 1.0 op_sel_hi:[1,0]
	v_pk_mul_f32 v[98:99], v[30:31], v[98:99]
	v_pk_add_f32 v[106:107], v[70:71], 1.0 op_sel_hi:[1,0]
	v_pk_fma_f32 v[104:105], v[108:109], v[104:105], v[72:73]
	v_pk_fma_f32 v[98:99], v[106:107], v[98:99], v[74:75]
	v_bfe_u32 v106, v104, 16, 1
	v_add3_u32 v104, v104, v106, s48
	v_bfe_u32 v106, v105, 16, 1
	v_lshrrev_b32_e32 v104, 16, v104
	v_add3_u32 v105, v105, v106, s48
	v_and_or_b32 v104, v105, s55, v104
	v_bfe_u32 v105, v98, 16, 1
	v_add3_u32 v98, v98, v105, s48
	v_bfe_u32 v105, v99, 16, 1
	v_lshrrev_b32_e32 v98, 16, v98
	v_add3_u32 v99, v99, v105, s48
	v_and_or_b32 v105, v99, s55, v98
	global_store_dwordx2 v[96:97], v[104:105], off offset:1024
	v_pk_mul_f32 v[104:105], v[128:129], v[0:1] op_sel_hi:[1,0]
	v_pk_add_f32 v[108:109], v[76:77], 1.0 op_sel_hi:[1,0]
	v_pk_mul_f32 v[104:105], v[32:33], v[104:105]
	v_pk_mul_f32 v[98:99], v[130:131], v[0:1] op_sel_hi:[1,0]
	v_pk_fma_f32 v[104:105], v[108:109], v[104:105], v[80:81]
	v_pk_mul_f32 v[98:99], v[34:35], v[98:99]
	v_bfe_u32 v0, v104, 16, 1
	v_pk_add_f32 v[106:107], v[78:79], 1.0 op_sel_hi:[1,0]
	v_add3_u32 v0, v104, v0, s48
	v_bfe_u32 v104, v105, 16, 1
	v_pk_fma_f32 v[98:99], v[106:107], v[98:99], v[82:83]
	v_lshrrev_b32_e32 v0, 16, v0
	v_add3_u32 v104, v105, v104, s48
	v_and_or_b32 v104, v104, s55, v0
	v_bfe_u32 v0, v98, 16, 1
	v_add3_u32 v0, v98, v0, s48
	v_bfe_u32 v98, v99, 16, 1
	v_lshrrev_b32_e32 v0, 16, v0
	v_add3_u32 v98, v99, v98, s48
	v_and_or_b32 v105, v98, s55, v0
	global_store_dwordx2 v[96:97], v[104:105], off offset:1536
	v_mov_b64_e32 v[110:111], v[94:95]
	v_mov_b64_e32 v[106:107], v[90:91]
	v_mov_b64_e32 v[98:99], v[86:87]
	v_mov_b64_e32 v[108:109], v[92:93]
	v_mov_b64_e32 v[104:105], v[88:89]
	v_mov_b64_e32 v[96:97], v[84:85]
	v_mov_b64_e32 v[116:117], v[150:151]
	v_mov_b64_e32 v[120:121], v[148:149]
	v_mov_b64_e32 v[124:125], v[146:147]
	s_cbranch_scc0 .LBB0_147

.LBB0_140:
	s_mov_b64 s[26:27], -1
	s_and_b64 vcc, exec, s[6:7]
	s_cbranch_vccz .LBB0_142
	v_and_b32_e32 v123, 0xffff0000, v133
	v_and_b32_e32 v122, 0xffff0000, v132
	v_and_b32_e32 v131, 0xffff0000, v125
	v_and_b32_e32 v130, 0xffff0000, v124
	v_lshlrev_b32_e32 v119, 16, v133
	v_lshlrev_b32_e32 v118, 16, v132
	v_pk_mul_f32 v[126:127], v[122:123], v[122:123]
	v_lshlrev_b32_e32 v129, 16, v125
	v_lshlrev_b32_e32 v128, 16, v124
	v_pk_mul_f32 v[124:125], v[130:131], v[130:131]
	v_lshlrev_b32_e32 v132, 16, v120
	v_and_b32_e32 v133, 0xffff0000, v120
	v_lshlrev_b32_e32 v134, 16, v121
	v_lshlrev_b32_e32 v158, 16, v116
	v_pk_fma_f32 v[126:127], v[118:119], v[118:119], v[126:127]
	v_pk_fma_f32 v[124:125], v[128:129], v[128:129], v[124:125]
	v_and_b32_e32 v135, 0xffff0000, v121
	v_mul_f32_e32 v159, v132, v132
	v_mul_f32_e32 v121, v133, v133
	v_mul_f32_e32 v0, v134, v134
	v_mov_b32_e32 v120, v158
	v_pk_add_f32 v[126:127], v[126:127], v[126:127] op_sel_hi:[0,1]
	v_pk_add_f32 v[124:125], v[124:125], v[124:125] op_sel_hi:[0,1]
	v_pk_fma_f32 v[160:161], v[134:135], v[134:135], v[0:1] op_sel_hi:[1,1,0]
	v_and_b32_e32 v164, 0xffff0000, v116
	v_lshlrev_b32_e32 v162, 16, v117
	v_and_b32_e32 v163, 0xffff0000, v117
	v_pk_add_f32 v[120:121], v[158:159], v[120:121]
	v_mul_f32_e32 v160, v164, v164
	v_mul_f32_e32 v124, v162, v162
	v_mul_f32_e32 v126, v163, v163
	v_mul_f32_e32 v116, v158, v158
	v_mov_b32_e32 v117, v121
	v_pk_add_f32 v[116:117], v[116:117], v[160:161]
	v_pk_add_f32 v[120:121], v[124:125], v[126:127]
	v_mov_b32_e32 v159, v164
	v_pk_add_f32 v[116:117], v[116:117], v[120:121]
	s_mov_b64 s[26:27], 0
	v_add_f32_e32 v0, v116, v117
	s_nop 1
	v_mov_b32_dpp v116, v0 quad_perm:[1,0,3,2] row_mask:0xf bank_mask:0xf
	s_waitcnt lgkmcnt(0)
	v_add_f32_e32 v0, v0, v116
	s_nop 1
	v_mov_b32_dpp v116, v0 quad_perm:[2,3,0,1] row_mask:0xf bank_mask:0xf
	s_waitcnt lgkmcnt(0)
	v_add_f32_e32 v0, v0, v116
	s_nop 1
	v_mov_b32_dpp v116, v0 row_half_mirror row_mask:0xf bank_mask:0xf
	s_waitcnt lgkmcnt(0)
	v_add_f32_e32 v0, v0, v116
	s_nop 1
	v_mov_b32_dpp v116, v0 row_mirror row_mask:0xf bank_mask:0xf
	s_waitcnt lgkmcnt(0)
	v_add_f32_e32 v0, v0, v116
	v_mov_b32_e32 v116, v0
	s_nop 1
	v_permlane16_swap_b32_e32 v116, v0
	s_waitcnt lgkmcnt(0)
	v_add_f32_e32 v0, v0, v116
	v_mov_b32_e32 v116, v0
	s_nop 1
	v_permlane32_swap_b32_e32 v116, v0
	s_waitcnt lgkmcnt(0)
	v_add_f32_e32 v0, v0, v116
	v_fmamk_f32 v0, v0, 0x3a800000, v196
	v_mul_f32_e32 v116, 0x4f800000, v0
	v_cmp_gt_f32_e32 vcc, s3, v0
	s_nop 1
	v_cndmask_b32_e32 v0, v0, v116, vcc
	v_sqrt_f32_e32 v116, v0
	s_nop 0
	v_add_u32_e32 v117, -1, v116
	v_fma_f32 v120, -v117, v116, v0
	v_cmp_ge_f32_e64 s[4:5], 0, v120
	v_add_u32_e32 v120, 1, v116
	s_nop 0
	v_cndmask_b32_e64 v117, v116, v117, s[4:5]
	v_fma_f32 v116, -v120, v116, v0
	v_cmp_lt_f32_e64 s[4:5], 0, v116
	s_nop 1
	v_cndmask_b32_e64 v116, v117, v120, s[4:5]
	v_mul_f32_e32 v117, 0x37800000, v116
	v_cndmask_b32_e32 v116, v116, v117, vcc
	v_cmp_class_f32_e32 vcc, v0, v197
	s_nop 1
	v_cndmask_b32_e32 v0, v116, v0, vcc
	v_div_scale_f32 v116, s[4:5], v0, v0, 1.0
	v_rcp_f32_e32 v117, v116
	s_ashr_i32 s5, s24, 31
	s_mov_b32 s4, s24
	v_fma_f32 v120, -v116, v117, 1.0
	v_fmac_f32_e32 v117, v120, v117
	v_div_scale_f32 v120, vcc, 1.0, v0, 1.0
	v_mul_f32_e32 v121, v120, v117
	v_fma_f32 v124, -v116, v121, v120
	v_fmac_f32_e32 v121, v124, v117
	v_fma_f32 v116, -v116, v121, v120
	v_div_fmas_f32 v116, v116, v117, v121
	v_div_fixup_f32 v0, v116, v0, 1.0
	v_mov_b32_e32 v116, v119
	v_mov_b32_e32 v117, v123
	v_pk_mul_f32 v[116:117], v[0:1], v[116:117] op_sel_hi:[0,1]
	v_mov_b32_e32 v119, v122
	v_pk_mul_f32 v[118:119], v[0:1], v[118:119] op_sel_hi:[0,1]
	v_pk_mul_f32 v[116:117], v[10:11], v[116:117]
	v_pk_mul_f32 v[118:119], v[8:9], v[118:119]
	v_pk_fma_f32 v[126:127], v[38:39], v[116:117], v[98:99]
	v_mov_b32_e32 v116, v129
	v_mov_b32_e32 v117, v131
	v_mov_b32_e32 v129, v130
	v_pk_fma_f32 v[124:125], v[36:37], v[118:119], v[96:97]
	v_pk_mul_f32 v[116:117], v[0:1], v[116:117] op_sel_hi:[0,1]
	v_pk_mul_f32 v[118:119], v[0:1], v[128:129] op_sel_hi:[0,1]
	v_pk_mul_f32 v[118:119], v[4:5], v[118:119]
	v_pk_mul_f32 v[116:117], v[6:7], v[116:117]
	v_pk_fma_f32 v[120:121], v[40:41], v[118:119], v[104:105]
	v_pk_fma_f32 v[122:123], v[42:43], v[116:117], v[106:107]
	v_pk_mul_f32 v[116:117], v[134:135], v[0:1] op_sel_hi:[1,0]
	v_pk_mul_f32 v[118:119], v[132:133], v[0:1] op_sel_hi:[1,0]
	v_pk_mul_f32 v[116:117], v[26:27], v[116:117]
	v_pk_mul_f32 v[128:129], v[24:25], v[118:119]
	v_pk_mul_f32 v[130:131], v[158:159], v[0:1] op_sel_hi:[1,0]
	v_pk_fma_f32 v[118:119], v[46:47], v[116:117], v[110:111]
	v_pk_fma_f32 v[116:117], v[44:45], v[128:129], v[108:109]
	v_pk_mul_f32 v[128:129], v[162:163], v[0:1] op_sel_hi:[1,0]
	v_pk_mul_f32 v[130:131], v[20:21], v[130:131]
	v_pk_mul_f32 v[128:129], v[22:23], v[128:129]
	v_pk_fma_f32 v[132:133], v[48:49], v[130:131], v[112:113]
	v_pk_fma_f32 v[134:135], v[50:51], v[128:129], v[114:115]
	global_store_dwordx4 v[142:143], v[124:127], off offset:-2048 nt
	v_mov_b64_e32 v[128:129], v[132:133]
	global_store_dwordx4 v[142:143], v[120:123], off offset:-1024 nt
	global_store_dwordx4 v[142:143], v[116:119], off nt
	global_store_dwordx4 v[142:143], v[132:135], off offset:1024 nt
	v_mov_b64_e32 v[130:131], v[134:135]

.LBB0_151:
	v_pk_mul_f32 v[2:3], v[66:67], v[66:67]
	v_pk_mul_f32 v[94:95], v[64:65], v[64:65]
	v_mul_f32_e32 v0, v56, v56
	v_pk_mov_b32 v[96:97], v[94:95], v[2:3] op_sel:[1,0]
	v_mov_b32_e32 v95, v3
	v_pk_add_f32 v[2:3], v[96:97], v[94:95]
	v_pk_mul_f32 v[94:95], v[62:63], v[62:63]
	v_pk_mul_f32 v[96:97], v[60:61], v[60:61]
	v_pk_add_f32 v[2:3], v[2:3], v[2:3] op_sel_hi:[0,1]
	v_pk_mov_b32 v[98:99], v[96:97], v[94:95] op_sel:[1,0]
	v_mov_b32_e32 v97, v95
	v_pk_add_f32 v[94:95], v[98:99], v[96:97]
	v_pk_fma_f32 v[96:97], v[56:57], v[56:57], v[0:1] op_sel_hi:[1,1,0]
	v_mul_f32_e32 v0, v58, v58
	v_pk_add_f32 v[94:95], v[94:95], v[94:95] op_sel_hi:[0,1]
	v_pk_fma_f32 v[98:99], v[58:59], v[58:59], v[0:1] op_sel_hi:[1,1,0]
	v_mul_f32_e32 v96, v20, v20
	v_mul_f32_e32 v98, v21, v21
	v_mul_f32_e32 v94, v22, v22
	v_mul_f32_e32 v2, v23, v23
	v_pk_add_f32 v[96:97], v[96:97], v[98:99]
	v_pk_add_f32 v[2:3], v[94:95], v[2:3]
	s_nop 0
	v_pk_add_f32 v[2:3], v[96:97], v[2:3]
	s_nop 0
	v_add_f32_e32 v0, v2, v3
	s_nop 1
	v_mov_b32_dpp v2, v0 quad_perm:[1,0,3,2] row_mask:0xf bank_mask:0xf
	s_waitcnt lgkmcnt(0)
	v_add_f32_e32 v0, v0, v2
	s_nop 1
	v_mov_b32_dpp v2, v0 quad_perm:[2,3,0,1] row_mask:0xf bank_mask:0xf
	s_waitcnt lgkmcnt(0)
	v_add_f32_e32 v0, v0, v2
	s_nop 1
	v_mov_b32_dpp v2, v0 row_half_mirror row_mask:0xf bank_mask:0xf
	s_waitcnt lgkmcnt(0)
	v_add_f32_e32 v0, v0, v2
	s_nop 1
	v_mov_b32_dpp v2, v0 row_mirror row_mask:0xf bank_mask:0xf
	s_waitcnt lgkmcnt(0)
	v_add_f32_e32 v0, v0, v2
	v_mov_b32_e32 v2, v0
	s_nop 1
	v_permlane16_swap_b32_e32 v2, v0
	s_waitcnt lgkmcnt(0)
	v_add_f32_e32 v0, v0, v2
	v_mov_b32_e32 v2, v0
	s_nop 1
	v_permlane32_swap_b32_e32 v2, v0
	s_waitcnt lgkmcnt(0)
	v_add_f32_e32 v0, v0, v2
	v_fmamk_f32 v0, v0, 0x3a800000, v196
	v_mul_f32_e32 v2, 0x4f800000, v0
	v_cmp_gt_f32_e32 vcc, s3, v0
	s_nop 1
	v_cndmask_b32_e32 v0, v0, v2, vcc
	v_sqrt_f32_e32 v94, v0
	v_pk_add_f32 v[2:3], v[42:43], 1.0 op_sel_hi:[1,0]
	v_add_u32_e32 v95, -1, v94
	v_add_u32_e32 v96, 1, v94
	v_fma_f32 v97, -v95, v94, v0
	v_fma_f32 v98, -v96, v94, v0
	v_cmp_ge_f32_e64 s[0:1], 0, v97
	s_nop 1
	v_cndmask_b32_e64 v94, v94, v95, s[0:1]
	v_cmp_lt_f32_e64 s[0:1], 0, v98
	s_nop 1
	v_cndmask_b32_e64 v94, v94, v96, s[0:1]
	v_mul_f32_e32 v95, 0x37800000, v94
	v_cndmask_b32_e32 v94, v94, v95, vcc
	v_cmp_class_f32_e32 vcc, v0, v197
	s_nop 1
	v_cndmask_b32_e32 v0, v94, v0, vcc
	v_div_scale_f32 v96, s[0:1], v0, v0, 1.0
	v_rcp_f32_e32 v97, v96
	v_div_scale_f32 v98, vcc, 1.0, v0, 1.0
	v_pk_add_f32 v[94:95], v[40:41], 1.0 op_sel_hi:[1,0]
	v_fma_f32 v99, -v96, v97, 1.0
	v_fmac_f32_e32 v97, v99, v97
	v_mul_f32_e32 v99, v98, v97
	v_fma_f32 v100, -v96, v99, v98
	v_fmac_f32_e32 v99, v100, v97
	v_fma_f32 v96, -v96, v99, v98
	v_div_fmas_f32 v96, v96, v97, v99
	v_div_fixup_f32 v0, v96, v0, 1.0
	v_pk_mul_f32 v[64:65], v[64:65], v[0:1] op_sel_hi:[1,0]
	v_pk_mul_f32 v[66:67], v[66:67], v[0:1] op_sel_hi:[1,0]
	v_pk_mul_f32 v[64:65], v[4:5], v[64:65]
	v_pk_mul_f32 v[66:67], v[6:7], v[66:67]
	v_pk_fma_f32 v[64:65], v[94:95], v[64:65], v[36:37]
	v_pk_fma_f32 v[2:3], v[2:3], v[66:67], v[38:39]
	v_bfe_u32 v66, v64, 16, 1
	v_add3_u32 v64, v64, v66, s48
	v_bfe_u32 v66, v65, 16, 1
	v_lshrrev_b32_e32 v64, 16, v64
	v_add3_u32 v65, v65, v66, s48
	v_and_or_b32 v64, v65, s55, v64
	v_bfe_u32 v65, v2, 16, 1
	v_add3_u32 v2, v2, v65, s48
	v_bfe_u32 v65, v3, 16, 1
	v_lshrrev_b32_e32 v2, 16, v2
	v_add3_u32 v3, v3, v65, s48
	v_and_or_b32 v65, v3, s55, v2
	v_pk_mul_f32 v[60:61], v[60:61], v[0:1] op_sel_hi:[1,0]
	global_store_dwordx2 v[86:87], v[64:65], off offset:-1536
	v_pk_mul_f32 v[2:3], v[62:63], v[0:1] op_sel_hi:[1,0]
	v_pk_mul_f32 v[60:61], v[8:9], v[60:61]
	v_pk_add_f32 v[64:65], v[28:29], 1.0 op_sel_hi:[1,0]
	v_pk_mul_f32 v[2:3], v[10:11], v[2:3]
	v_pk_add_f32 v[62:63], v[30:31], 1.0 op_sel_hi:[1,0]
	v_pk_fma_f32 v[60:61], v[64:65], v[60:61], v[44:45]
	v_pk_fma_f32 v[2:3], v[62:63], v[2:3], v[46:47]
	v_bfe_u32 v62, v60, 16, 1
	v_add3_u32 v60, v60, v62, s48
	v_bfe_u32 v62, v61, 16, 1
	v_lshrrev_b32_e32 v60, 16, v60
	v_add3_u32 v61, v61, v62, s48
	v_and_or_b32 v60, v61, s55, v60
	v_bfe_u32 v61, v2, 16, 1
	v_add3_u32 v2, v2, v61, s48
	v_bfe_u32 v61, v3, 16, 1
	v_lshrrev_b32_e32 v2, 16, v2
	v_add3_u32 v3, v3, v61, s48
	v_and_or_b32 v61, v3, s55, v2
	v_pk_mul_f32 v[56:57], v[56:57], v[0:1] op_sel_hi:[1,0]
	global_store_dwordx2 v[86:87], v[60:61], off offset:-1024
	v_pk_mul_f32 v[2:3], v[58:59], v[0:1] op_sel_hi:[1,0]
	v_pk_mul_f32 v[56:57], v[12:13], v[56:57]
	v_pk_add_f32 v[60:61], v[24:25], 1.0 op_sel_hi:[1,0]
	v_pk_mul_f32 v[2:3], v[14:15], v[2:3]
	v_pk_add_f32 v[58:59], v[26:27], 1.0 op_sel_hi:[1,0]
	v_pk_fma_f32 v[56:57], v[60:61], v[56:57], v[52:53]
	v_pk_fma_f32 v[2:3], v[58:59], v[2:3], v[54:55]
	v_bfe_u32 v58, v56, 16, 1
	v_add3_u32 v56, v56, v58, s48
	v_bfe_u32 v58, v57, 16, 1
	v_lshrrev_b32_e32 v56, 16, v56
	v_add3_u32 v57, v57, v58, s48
	v_and_or_b32 v56, v57, s55, v56
	v_bfe_u32 v57, v2, 16, 1
	v_add3_u32 v2, v2, v57, s48
	v_bfe_u32 v57, v3, 16, 1
	v_lshrrev_b32_e32 v2, 16, v2
	v_add3_u32 v3, v3, v57, s48
	v_and_or_b32 v57, v3, s55, v2
	v_pk_mul_f32 v[20:21], v[20:21], v[0:1] op_sel_hi:[1,0]
	global_store_dwordx2 v[86:87], v[56:57], off offset:-512
	v_pk_mul_f32 v[20:21], v[16:17], v[20:21]
	v_pk_add_f32 v[56:57], v[32:33], 1.0 op_sel_hi:[1,0]
	v_pk_mul_f32 v[2:3], v[22:23], v[0:1] op_sel_hi:[1,0]
	v_pk_fma_f32 v[20:21], v[56:57], v[20:21], v[48:49]
	v_pk_mul_f32 v[2:3], v[18:19], v[2:3]
	v_bfe_u32 v0, v20, 16, 1
	v_pk_add_f32 v[22:23], v[34:35], 1.0 op_sel_hi:[1,0]
	v_add3_u32 v0, v20, v0, s48
	v_bfe_u32 v20, v21, 16, 1
	v_pk_fma_f32 v[2:3], v[22:23], v[2:3], v[50:51]
	v_lshrrev_b32_e32 v0, 16, v0
	v_add3_u32 v20, v21, v20, s48
	v_and_or_b32 v20, v20, s55, v0
	v_bfe_u32 v0, v2, 16, 1
	v_add3_u32 v0, v2, v0, s48
	v_bfe_u32 v2, v3, 16, 1
	v_lshrrev_b32_e32 v0, 16, v0
	v_add3_u32 v2, v3, v2, s48
	v_and_or_b32 v21, v2, s55, v0
	global_store_dwordx2 v[86:87], v[20:21], off
	s_waitcnt vmcnt(4)
	v_mov_b64_e32 v[20:21], v[80:81]
	v_mov_b64_e32 v[56:57], v[76:77]
	v_mov_b64_e32 v[60:61], v[72:73]
	v_mov_b64_e32 v[64:65], v[68:69]
	v_lshl_add_u64 v[86:87], v[86:87], 0, s[60:61]
	s_and_b64 vcc, exec, s[24:25]
	s_mov_b64 s[0:1], s[6:7]
	v_mov_b64_e32 v[22:23], v[82:83]
	v_mov_b64_e32 v[58:59], v[78:79]
	v_mov_b64_e32 v[62:63], v[74:75]
	v_mov_b64_e32 v[66:67], v[70:71]
	s_cbranch_vccnz .LBB0_156

.LBB0_825:
	v_pk_mul_f32 v[88:89], v[130:131], v[130:131]
	v_pk_mul_f32 v[90:91], v[128:129], v[128:129]
	v_pk_mul_f32 v[84:85], v[122:123], v[122:123]
	v_pk_mul_f32 v[86:87], v[120:121], v[120:121]
	v_pk_mov_b32 v[92:93], v[90:91], v[88:89] op_sel:[1,0]
	v_mov_b32_e32 v91, v89
	v_pk_add_f32 v[88:89], v[92:93], v[90:91]
	v_pk_mov_b32 v[90:91], v[86:87], v[84:85] op_sel:[1,0]
	v_mov_b32_e32 v87, v85
	v_mul_f32_e32 v0, v116, v116
	v_pk_add_f32 v[84:85], v[90:91], v[86:87]
	v_pk_fma_f32 v[86:87], v[116:117], v[116:117], v[0:1] op_sel_hi:[1,1,0]
	v_mul_f32_e32 v0, v118, v118
	v_pk_add_f32 v[88:89], v[88:89], v[88:89] op_sel_hi:[0,1]
	v_pk_add_f32 v[84:85], v[84:85], v[84:85] op_sel_hi:[0,1]
	v_pk_fma_f32 v[90:91], v[118:119], v[118:119], v[0:1] op_sel_hi:[1,1,0]
	v_mul_f32_e32 v86, v132, v132
	v_mul_f32_e32 v90, v133, v133
	v_mul_f32_e32 v88, v134, v134
	v_mul_f32_e32 v84, v135, v135
	v_pk_add_f32 v[86:87], v[86:87], v[90:91]
	v_pk_add_f32 v[84:85], v[88:89], v[84:85]
	s_lshl_b64 s[30:31], s[4:5], 11
	v_pk_add_f32 v[84:85], v[86:87], v[84:85]
	v_pk_add_f32 v[92:93], v[52:53], 1.0 op_sel_hi:[1,0]
	v_add_f32_e32 v0, v84, v85
	s_nop 1
	v_mov_b32_dpp v84, v0 quad_perm:[1,0,3,2] row_mask:0xf bank_mask:0xf
	s_add_u32 s24, s24, 0x1000
	s_waitcnt vmcnt(0)
	v_mov_b64_e32 v[96:97], v[112:113]
	s_addc_u32 s25, s25, 0
	v_lshl_add_u64 v[142:143], v[142:143], 0, s[64:65]
	s_waitcnt lgkmcnt(0)
	v_add_f32_e32 v0, v0, v84
	s_nop 1
	v_mov_b32_dpp v84, v0 quad_perm:[2,3,0,1] row_mask:0xf bank_mask:0xf
	s_mov_b64 s[58:59], s[26:27]
	v_mov_b64_e32 v[98:99], v[114:115]
	v_mov_b64_e32 v[132:133], v[2:3]
	s_waitcnt lgkmcnt(0)
	v_add_f32_e32 v0, v0, v84
	s_nop 1
	v_mov_b32_dpp v84, v0 row_half_mirror row_mask:0xf bank_mask:0xf
	s_waitcnt lgkmcnt(0)
	v_add_f32_e32 v0, v0, v84
	s_nop 1
	v_mov_b32_dpp v84, v0 row_mirror row_mask:0xf bank_mask:0xf
	s_waitcnt lgkmcnt(0)
	v_add_f32_e32 v0, v0, v84
	v_mov_b32_e32 v84, v0
	s_nop 1
	v_permlane16_swap_b32_e32 v84, v0
	s_waitcnt lgkmcnt(0)
	v_add_f32_e32 v0, v0, v84
	v_mov_b32_e32 v84, v0
	s_nop 1
	v_permlane32_swap_b32_e32 v84, v0
	s_waitcnt lgkmcnt(0)
	v_add_f32_e32 v0, v0, v84
	v_fmamk_f32 v0, v0, 0x3a800000, v196
	v_mul_f32_e32 v84, 0x4f800000, v0
	v_cmp_gt_f32_e32 vcc, s3, v0
	s_nop 1
	v_cndmask_b32_e32 v0, v0, v84, vcc
	v_sqrt_f32_e32 v84, v0
	s_nop 0
	v_add_u32_e32 v85, -1, v84
	v_add_u32_e32 v86, 1, v84
	v_fma_f32 v87, -v85, v84, v0
	v_fma_f32 v88, -v86, v84, v0
	v_cmp_ge_f32_e64 s[4:5], 0, v87
	s_nop 1
	v_cndmask_b32_e64 v84, v84, v85, s[4:5]
	v_cmp_lt_f32_e64 s[4:5], 0, v88
	s_nop 1
	v_cndmask_b32_e64 v84, v84, v86, s[4:5]
	v_mul_f32_e32 v85, 0x37800000, v84
	v_cndmask_b32_e32 v84, v84, v85, vcc
	v_cmp_class_f32_e32 vcc, v0, v197
	s_nop 1
	v_cndmask_b32_e32 v0, v84, v0, vcc
	v_div_scale_f32 v86, s[4:5], v0, v0, 1.0
	v_rcp_f32_e32 v87, v86
	v_div_scale_f32 v88, vcc, 1.0, v0, 1.0
	v_lshl_add_u64 v[84:85], v[140:141], 0, s[30:31]
	v_fma_f32 v89, -v86, v87, 1.0
	v_fmac_f32_e32 v87, v89, v87
	v_mul_f32_e32 v89, v88, v87
	v_fma_f32 v90, -v86, v89, v88
	v_fmac_f32_e32 v89, v90, v87
	v_fma_f32 v86, -v86, v89, v88
	v_div_fmas_f32 v86, v86, v87, v89
	v_div_fixup_f32 v0, v86, v0, 1.0
	v_pk_mul_f32 v[88:89], v[128:129], v[0:1] op_sel_hi:[1,0]
	v_pk_mul_f32 v[86:87], v[130:131], v[0:1] op_sel_hi:[1,0]
	v_pk_mul_f32 v[88:89], v[12:13], v[88:89]
	v_pk_mul_f32 v[86:87], v[14:15], v[86:87]
	v_pk_add_f32 v[90:91], v[54:55], 1.0 op_sel_hi:[1,0]
	v_pk_fma_f32 v[88:89], v[92:93], v[88:89], v[56:57]
	v_pk_fma_f32 v[86:87], v[90:91], v[86:87], v[58:59]
	v_bfe_u32 v90, v88, 16, 1
	v_add3_u32 v88, v88, v90, s48
	v_bfe_u32 v90, v89, 16, 1
	v_lshrrev_b32_e32 v88, 16, v88
	v_add3_u32 v89, v89, v90, s48
	v_and_or_b32 v88, v89, s55, v88
	v_bfe_u32 v89, v86, 16, 1
	v_add3_u32 v86, v86, v89, s48
	v_bfe_u32 v89, v87, 16, 1
	v_lshrrev_b32_e32 v86, 16, v86
	v_add3_u32 v87, v87, v89, s48
	v_and_or_b32 v89, v87, s55, v86
	global_store_dwordx2 v[84:85], v[88:89], off
	v_pk_mul_f32 v[88:89], v[120:121], v[0:1] op_sel_hi:[1,0]
	v_pk_mul_f32 v[86:87], v[122:123], v[0:1] op_sel_hi:[1,0]
	v_pk_mul_f32 v[88:89], v[16:17], v[88:89]
	v_pk_add_f32 v[92:93], v[60:61], 1.0 op_sel_hi:[1,0]
	v_pk_mul_f32 v[86:87], v[18:19], v[86:87]
	v_pk_add_f32 v[90:91], v[62:63], 1.0 op_sel_hi:[1,0]
	v_pk_fma_f32 v[88:89], v[92:93], v[88:89], v[64:65]
	v_pk_fma_f32 v[86:87], v[90:91], v[86:87], v[66:67]
	v_bfe_u32 v90, v88, 16, 1
	v_add3_u32 v88, v88, v90, s48
	v_bfe_u32 v90, v89, 16, 1
	v_lshrrev_b32_e32 v88, 16, v88
	v_add3_u32 v89, v89, v90, s48
	v_and_or_b32 v88, v89, s55, v88
	v_bfe_u32 v89, v86, 16, 1
	v_add3_u32 v86, v86, v89, s48
	v_bfe_u32 v89, v87, 16, 1
	v_lshrrev_b32_e32 v86, 16, v86
	v_add3_u32 v87, v87, v89, s48
	v_and_or_b32 v89, v87, s55, v86
	global_store_dwordx2 v[84:85], v[88:89], off offset:512
	v_pk_mul_f32 v[88:89], v[116:117], v[0:1] op_sel_hi:[1,0]
	v_pk_mul_f32 v[86:87], v[118:119], v[0:1] op_sel_hi:[1,0]
	v_pk_mul_f32 v[88:89], v[28:29], v[88:89]
	v_pk_add_f32 v[92:93], v[68:69], 1.0 op_sel_hi:[1,0]
	v_pk_mul_f32 v[86:87], v[30:31], v[86:87]
	v_pk_add_f32 v[90:91], v[70:71], 1.0 op_sel_hi:[1,0]
	v_pk_fma_f32 v[88:89], v[92:93], v[88:89], v[72:73]
	v_pk_fma_f32 v[86:87], v[90:91], v[86:87], v[74:75]
	v_bfe_u32 v90, v88, 16, 1
	v_add3_u32 v88, v88, v90, s48
	v_bfe_u32 v90, v89, 16, 1
	v_lshrrev_b32_e32 v88, 16, v88
	v_add3_u32 v89, v89, v90, s48
	v_and_or_b32 v88, v89, s55, v88
	v_bfe_u32 v89, v86, 16, 1
	v_add3_u32 v86, v86, v89, s48
	v_bfe_u32 v89, v87, 16, 1
	v_lshrrev_b32_e32 v86, 16, v86
	v_add3_u32 v87, v87, v89, s48
	v_and_or_b32 v89, v87, s55, v86
	global_store_dwordx2 v[84:85], v[88:89], off offset:1024
	v_pk_mul_f32 v[88:89], v[124:125], v[0:1] op_sel_hi:[1,0]
	v_pk_add_f32 v[92:93], v[76:77], 1.0 op_sel_hi:[1,0]
	v_pk_mul_f32 v[88:89], v[32:33], v[88:89]
	v_pk_mul_f32 v[86:87], v[126:127], v[0:1] op_sel_hi:[1,0]
	v_pk_fma_f32 v[88:89], v[92:93], v[88:89], v[80:81]
	v_pk_mul_f32 v[86:87], v[34:35], v[86:87]
	v_bfe_u32 v0, v88, 16, 1
	v_pk_add_f32 v[90:91], v[78:79], 1.0 op_sel_hi:[1,0]
	v_add3_u32 v0, v88, v0, s48
	v_bfe_u32 v88, v89, 16, 1
	v_pk_fma_f32 v[86:87], v[90:91], v[86:87], v[82:83]
	v_lshrrev_b32_e32 v0, 16, v0
	v_add3_u32 v88, v89, v88, s48
	v_and_or_b32 v88, v88, s55, v0
	v_bfe_u32 v0, v86, 16, 1
	v_add3_u32 v0, v86, v0, s48
	v_bfe_u32 v86, v87, 16, 1
	v_lshrrev_b32_e32 v0, 16, v0
	v_add3_u32 v86, v87, v86, s48
	v_and_or_b32 v89, v86, s55, v0
	global_store_dwordx2 v[84:85], v[88:89], off offset:1536
	v_mov_b64_e32 v[92:93], v[108:109]
	v_mov_b64_e32 v[88:89], v[104:105]
	v_mov_b64_e32 v[84:85], v[100:101]
	s_andn2_b64 vcc, exec, s[28:29]
	v_mov_b64_e32 v[94:95], v[110:111]
	v_mov_b64_e32 v[90:91], v[106:107]
	v_mov_b64_e32 v[86:87], v[102:103]
	v_mov_b64_e32 v[116:117], v[148:149]
	v_mov_b64_e32 v[120:121], v[146:147]
	v_mov_b64_e32 v[128:129], v[144:145]
	s_cbranch_vccz .LBB0_854

.LBB0_847:
	s_mov_b64 s[30:31], -1
	s_and_b64 vcc, exec, s[6:7]
	s_cbranch_vccz .LBB0_849
	v_lshlrev_b32_e32 v119, 16, v133
	v_lshlrev_b32_e32 v118, 16, v132
	v_and_b32_e32 v123, 0xffff0000, v133
	v_and_b32_e32 v122, 0xffff0000, v132
	v_and_b32_e32 v133, 0xffff0000, v129
	v_and_b32_e32 v132, 0xffff0000, v128
	v_pk_mul_f32 v[124:125], v[122:123], v[122:123]
	v_lshlrev_b32_e32 v127, 16, v129
	v_lshlrev_b32_e32 v126, 16, v128
	v_pk_mul_f32 v[128:129], v[132:133], v[132:133]
	v_lshlrev_b32_e32 v134, 16, v120
	v_and_b32_e32 v135, 0xffff0000, v120
	v_lshlrev_b32_e32 v156, 16, v121
	v_lshlrev_b32_e32 v158, 16, v116
	v_pk_fma_f32 v[124:125], v[118:119], v[118:119], v[124:125]
	v_pk_fma_f32 v[128:129], v[126:127], v[126:127], v[128:129]
	v_and_b32_e32 v157, 0xffff0000, v121
	v_mul_f32_e32 v159, v134, v134
	v_mul_f32_e32 v121, v135, v135
	v_mul_f32_e32 v0, v156, v156
	v_mov_b32_e32 v120, v158
	v_pk_add_f32 v[124:125], v[124:125], v[124:125] op_sel_hi:[0,1]
	v_pk_add_f32 v[128:129], v[128:129], v[128:129] op_sel_hi:[0,1]
	v_pk_fma_f32 v[130:131], v[156:157], v[156:157], v[0:1] op_sel_hi:[1,1,0]
	v_and_b32_e32 v162, 0xffff0000, v116
	v_lshlrev_b32_e32 v160, 16, v117
	v_and_b32_e32 v161, 0xffff0000, v117
	v_pk_add_f32 v[120:121], v[158:159], v[120:121]
	v_mul_f32_e32 v130, v162, v162
	v_mul_f32_e32 v128, v160, v160
	v_mul_f32_e32 v124, v161, v161
	v_mul_f32_e32 v116, v158, v158
	v_mov_b32_e32 v117, v121
	v_pk_add_f32 v[116:117], v[116:117], v[130:131]
	v_pk_add_f32 v[120:121], v[128:129], v[124:125]
	v_mov_b32_e32 v159, v162
	v_pk_add_f32 v[116:117], v[116:117], v[120:121]
	s_mov_b64 s[30:31], 0
	v_add_f32_e32 v0, v116, v117
	s_nop 1
	v_mov_b32_dpp v116, v0 quad_perm:[1,0,3,2] row_mask:0xf bank_mask:0xf
	s_waitcnt lgkmcnt(0)
	v_add_f32_e32 v0, v0, v116
	s_nop 1
	v_mov_b32_dpp v116, v0 quad_perm:[2,3,0,1] row_mask:0xf bank_mask:0xf
	s_waitcnt lgkmcnt(0)
	v_add_f32_e32 v0, v0, v116
	s_nop 1
	v_mov_b32_dpp v116, v0 row_half_mirror row_mask:0xf bank_mask:0xf
	s_waitcnt lgkmcnt(0)
	v_add_f32_e32 v0, v0, v116
	s_nop 1
	v_mov_b32_dpp v116, v0 row_mirror row_mask:0xf bank_mask:0xf
	s_waitcnt lgkmcnt(0)
	v_add_f32_e32 v0, v0, v116
	v_mov_b32_e32 v116, v0
	s_nop 1
	v_permlane16_swap_b32_e32 v116, v0
	s_waitcnt lgkmcnt(0)
	v_add_f32_e32 v0, v0, v116
	v_mov_b32_e32 v116, v0
	s_nop 1
	v_permlane32_swap_b32_e32 v116, v0
	s_waitcnt lgkmcnt(0)
	v_add_f32_e32 v0, v0, v116
	v_fmamk_f32 v0, v0, 0x3a800000, v196
	v_mul_f32_e32 v116, 0x4f800000, v0
	v_cmp_gt_f32_e32 vcc, s3, v0
	s_nop 1
	v_cndmask_b32_e32 v0, v0, v116, vcc
	v_sqrt_f32_e32 v116, v0
	s_nop 0
	v_add_u32_e32 v117, -1, v116
	v_fma_f32 v120, -v117, v116, v0
	v_cmp_ge_f32_e64 s[4:5], 0, v120
	v_add_u32_e32 v120, 1, v116
	s_nop 0
	v_cndmask_b32_e64 v117, v116, v117, s[4:5]
	v_fma_f32 v116, -v120, v116, v0
	v_cmp_lt_f32_e64 s[4:5], 0, v116
	s_nop 1
	v_cndmask_b32_e64 v116, v117, v120, s[4:5]
	v_mul_f32_e32 v117, 0x37800000, v116
	v_cndmask_b32_e32 v116, v116, v117, vcc
	v_cmp_class_f32_e32 vcc, v0, v197
	s_nop 1
	v_cndmask_b32_e32 v0, v116, v0, vcc
	v_div_scale_f32 v116, s[4:5], v0, v0, 1.0
	v_rcp_f32_e32 v117, v116
	s_ashr_i32 s5, s58, 31
	s_mov_b32 s4, s58
	v_fma_f32 v120, -v116, v117, 1.0
	v_fmac_f32_e32 v117, v120, v117
	v_div_scale_f32 v120, vcc, 1.0, v0, 1.0
	v_mul_f32_e32 v121, v120, v117
	v_fma_f32 v124, -v116, v121, v120
	v_fmac_f32_e32 v121, v124, v117
	v_fma_f32 v116, -v116, v121, v120
	v_div_fmas_f32 v116, v116, v117, v121
	v_div_fixup_f32 v0, v116, v0, 1.0
	v_mov_b32_e32 v116, v119
	v_mov_b32_e32 v117, v123
	v_pk_mul_f32 v[116:117], v[0:1], v[116:117] op_sel_hi:[0,1]
	v_mov_b32_e32 v119, v122
	v_pk_mul_f32 v[118:119], v[0:1], v[118:119] op_sel_hi:[0,1]
	v_pk_mul_f32 v[116:117], v[10:11], v[116:117]
	v_pk_mul_f32 v[118:119], v[8:9], v[118:119]
	v_pk_fma_f32 v[130:131], v[38:39], v[116:117], v[86:87]
	v_mov_b32_e32 v116, v127
	v_mov_b32_e32 v117, v133
	v_mov_b32_e32 v127, v132
	v_pk_fma_f32 v[128:129], v[36:37], v[118:119], v[84:85]
	v_pk_mul_f32 v[116:117], v[0:1], v[116:117] op_sel_hi:[0,1]
	v_pk_mul_f32 v[118:119], v[0:1], v[126:127] op_sel_hi:[0,1]
	v_pk_mul_f32 v[118:119], v[4:5], v[118:119]
	v_pk_mul_f32 v[116:117], v[6:7], v[116:117]
	v_pk_fma_f32 v[120:121], v[40:41], v[118:119], v[88:89]
	v_pk_fma_f32 v[122:123], v[42:43], v[116:117], v[90:91]
	v_pk_mul_f32 v[116:117], v[156:157], v[0:1] op_sel_hi:[1,0]
	v_pk_mul_f32 v[118:119], v[134:135], v[0:1] op_sel_hi:[1,0]
	v_pk_mul_f32 v[116:117], v[26:27], v[116:117]
	v_pk_mul_f32 v[124:125], v[24:25], v[118:119]
	v_pk_mul_f32 v[126:127], v[158:159], v[0:1] op_sel_hi:[1,0]
	v_pk_fma_f32 v[118:119], v[46:47], v[116:117], v[94:95]
	v_pk_fma_f32 v[116:117], v[44:45], v[124:125], v[92:93]
	v_pk_mul_f32 v[124:125], v[160:161], v[0:1] op_sel_hi:[1,0]
	v_pk_mul_f32 v[126:127], v[20:21], v[126:127]
	v_pk_mul_f32 v[124:125], v[22:23], v[124:125]
	v_pk_fma_f32 v[132:133], v[48:49], v[126:127], v[96:97]
	v_pk_fma_f32 v[134:135], v[50:51], v[124:125], v[98:99]
	global_store_dwordx4 v[142:143], v[128:131], off offset:-2048 nt
	v_mov_b64_e32 v[124:125], v[132:133]
	global_store_dwordx4 v[142:143], v[120:123], off offset:-1024 nt
	global_store_dwordx4 v[142:143], v[116:119], off nt
	global_store_dwordx4 v[142:143], v[132:135], off offset:1024 nt
	v_mov_b64_e32 v[126:127], v[134:135]

.LBB0_1073:
	s_and_b64 vcc, exec, s[0:1]
	s_cbranch_vccnz .LBB0_1059
	v_lshlrev_b32_e32 v97, 16, v79
	v_lshlrev_b32_e32 v96, 16, v78
	v_and_b32_e32 v79, 0xffff0000, v79
	v_and_b32_e32 v78, 0xffff0000, v78
	v_pk_mul_f32 v[98:99], v[78:79], v[78:79]
	v_lshlrev_b32_e32 v101, 16, v77
	v_pk_fma_f32 v[98:99], v[96:97], v[96:97], v[98:99]
	v_lshlrev_b32_e32 v100, 16, v76
	v_and_b32_e32 v77, 0xffff0000, v77
	v_and_b32_e32 v76, 0xffff0000, v76
	v_pk_add_f32 v[98:99], v[98:99], v[98:99] op_sel_hi:[0,1]
	v_pk_mul_f32 v[102:103], v[76:77], v[76:77]
	v_lshlrev_b32_e32 v104, 16, v74
	v_and_b32_e32 v105, 0xffff0000, v74
	v_lshlrev_b32_e32 v74, 16, v75
	v_lshlrev_b32_e32 v106, 16, v72
	v_pk_fma_f32 v[102:103], v[100:101], v[100:101], v[102:103]
	v_and_b32_e32 v75, 0xffff0000, v75
	v_mul_f32_e32 v107, v104, v104
	v_mul_f32_e32 v109, v105, v105
	v_mul_f32_e32 v98, v74, v74
	v_mov_b32_e32 v108, v106
	v_pk_add_f32 v[102:103], v[102:103], v[102:103] op_sel_hi:[0,1]
	v_pk_fma_f32 v[110:111], v[74:75], v[74:75], v[98:99] op_sel_hi:[1,1,0]
	v_and_b32_e32 v114, 0xffff0000, v72
	v_lshlrev_b32_e32 v72, 16, v73
	v_and_b32_e32 v73, 0xffff0000, v73
	v_pk_add_f32 v[108:109], v[106:107], v[108:109]
	v_mul_f32_e32 v110, v114, v114
	v_mul_f32_e32 v102, v72, v72
	v_mul_f32_e32 v98, v73, v73
	v_mul_f32_e32 v112, v106, v106
	v_mov_b32_e32 v113, v109
	v_pk_add_f32 v[108:109], v[112:113], v[110:111]
	v_pk_add_f32 v[98:99], v[102:103], v[98:99]
	s_nop 0
	v_pk_add_f32 v[98:99], v[108:109], v[98:99]
	s_nop 0
	v_add_f32_e32 v98, v98, v99
	s_nop 1
	v_mov_b32_dpp v99, v98 quad_perm:[1,0,3,2] row_mask:0xf bank_mask:0xf
	s_waitcnt lgkmcnt(0)
	v_add_f32_e32 v98, v98, v99
	s_nop 1
	v_mov_b32_dpp v99, v98 quad_perm:[2,3,0,1] row_mask:0xf bank_mask:0xf
	s_waitcnt lgkmcnt(0)
	v_add_f32_e32 v98, v98, v99
	s_nop 1
	v_mov_b32_dpp v99, v98 row_half_mirror row_mask:0xf bank_mask:0xf
	s_waitcnt lgkmcnt(0)
	v_add_f32_e32 v98, v98, v99
	s_nop 1
	v_mov_b32_dpp v99, v98 row_mirror row_mask:0xf bank_mask:0xf
	s_waitcnt lgkmcnt(0)
	v_add_f32_e32 v98, v98, v99
	v_mov_b32_e32 v99, v98
	s_nop 1
	v_permlane16_swap_b32_e32 v99, v98
	s_waitcnt lgkmcnt(0)
	v_add_f32_e32 v98, v98, v99
	v_mov_b32_e32 v99, v98
	s_nop 1
	v_permlane32_swap_b32_e32 v99, v98
	s_waitcnt lgkmcnt(0)
	v_add_f32_e32 v98, v98, v99
	v_fmamk_f32 v98, v98, 0x3a800000, v94
	v_mul_f32_e32 v99, 0x4f800000, v98
	v_cmp_gt_f32_e32 vcc, s7, v98
	s_nop 1
	v_cndmask_b32_e32 v98, v98, v99, vcc
	v_sqrt_f32_e32 v99, v98
	s_nop 0
	v_add_u32_e32 v102, -1, v99
	v_fma_f32 v103, -v102, v99, v98
	v_cmp_ge_f32_e64 s[2:3], 0, v103
	v_add_u32_e32 v103, 1, v99
	s_nop 0
	v_cndmask_b32_e64 v102, v99, v102, s[2:3]
	v_fma_f32 v99, -v103, v99, v98
	v_cmp_lt_f32_e64 s[2:3], 0, v99
	s_nop 1
	v_cndmask_b32_e64 v99, v102, v103, s[2:3]
	v_mul_f32_e32 v102, 0x37800000, v99
	v_cndmask_b32_e32 v99, v99, v102, vcc
	v_cmp_class_f32_e32 vcc, v98, v95
	s_nop 1
	v_cndmask_b32_e32 v98, v99, v98, vcc
	v_div_scale_f32 v99, s[2:3], v98, v98, 1.0
	v_rcp_f32_e32 v102, v99
	s_nop 0
	v_fma_f32 v103, -v99, v102, 1.0
	v_fmac_f32_e32 v102, v103, v102
	v_div_scale_f32 v103, vcc, 1.0, v98, 1.0
	v_mul_f32_e32 v107, v103, v102
	v_fma_f32 v108, -v99, v107, v103
	v_fmac_f32_e32 v107, v108, v102
	v_fma_f32 v99, -v99, v107, v103
	v_div_fmas_f32 v99, v99, v102, v107
	v_div_fixup_f32 v98, v99, v98, 1.0
	v_mov_b32_e32 v102, v97
	v_mov_b32_e32 v103, v79
	v_mov_b32_e32 v97, v78
	v_pk_mul_f32 v[102:103], v[98:99], v[102:103] op_sel_hi:[0,1]
	v_pk_mul_f32 v[78:79], v[98:99], v[96:97] op_sel_hi:[0,1]
	v_pk_mul_f32 v[78:79], v[4:5], v[78:79]
	v_pk_mul_f32 v[96:97], v[6:7], v[102:103]
	v_pk_fma_f32 v[28:29], v[32:33], v[78:79], v[28:29]
	v_pk_fma_f32 v[30:31], v[34:35], v[96:97], v[30:31]
	global_store_dwordx4 v[68:69], v[28:31], off offset:-2048 nt
	v_mov_b32_e32 v107, v114
	s_nop 0
	v_mov_b32_e32 v28, v101
	v_mov_b32_e32 v29, v77
	v_mov_b32_e32 v101, v76
	v_pk_mul_f32 v[28:29], v[98:99], v[28:29] op_sel_hi:[0,1]
	v_pk_mul_f32 v[30:31], v[98:99], v[100:101] op_sel_hi:[0,1]
	v_pk_mul_f32 v[30:31], v[0:1], v[30:31]
	v_pk_mul_f32 v[28:29], v[2:3], v[28:29]
	v_pk_fma_f32 v[24:25], v[36:37], v[30:31], v[24:25]
	v_pk_fma_f32 v[26:27], v[38:39], v[28:29], v[26:27]
	global_store_dwordx4 v[68:69], v[24:27], off offset:-1024 nt
	s_nop 1
	v_pk_mul_f32 v[24:25], v[74:75], v[98:99] op_sel_hi:[1,0]
	v_pk_mul_f32 v[26:27], v[104:105], v[98:99] op_sel_hi:[1,0]
	v_pk_mul_f32 v[24:25], v[14:15], v[24:25]
	v_pk_mul_f32 v[26:27], v[12:13], v[26:27]
	v_pk_fma_f32 v[22:23], v[42:43], v[24:25], v[22:23]
	v_pk_fma_f32 v[20:21], v[40:41], v[26:27], v[20:21]
	global_store_dwordx4 v[68:69], v[20:23], off nt
	s_nop 1
	v_pk_mul_f32 v[20:21], v[72:73], v[98:99] op_sel_hi:[1,0]
	v_pk_mul_f32 v[22:23], v[106:107], v[98:99] op_sel_hi:[1,0]
	v_pk_mul_f32 v[20:21], v[10:11], v[20:21]
	v_pk_mul_f32 v[22:23], v[8:9], v[22:23]
	v_pk_fma_f32 v[18:19], v[46:47], v[20:21], v[18:19]
	v_pk_fma_f32 v[16:17], v[44:45], v[22:23], v[16:17]
	global_store_dwordx4 v[68:69], v[16:19], off offset:1024 nt
	s_branch .LBB0_1059
